# no grid barrier between the output projection of row group 0 and the input projection of row group 1 (the second reads nothing the first wrote), on top of the barrier without per-XCD relay
# speedup vs baseline: 1.0034x; 1.0034x over previous
; __device__ __forceinline__ int opaque_tid(int wave_s) { int t; asm volatile("v_mbcnt_lo_u32_b32 %0, -1, 0\n\tv_mbcnt_hi_u32_b32 %0, -1, %0" : "=v"(t)); return (wave_s << 6) | t; }
; #define PH_BEGIN(k) if (lo <= ph && ph < hi) { __syncthreads(); const int tid = opaque_tid(wave_s); const int lane = tid & 63; const int wave = __builtin_amdgcn_readfirstlane(tid >> 6); (void)lane; (void)wave; unsigned char* const ws = (unsigned char*)pt.in(33); float* const out = (float*)pt.in(32); (void)out;
; __global__ void __launch_bounds__(512, 2) hse_fwd(Params P) {
;     ...
;             PH_BEGIN(8)
;             { pg8::Gemm gm{merged, wt + WT_O, GPR, 2048, 2048, 2048, 2048}; pg8::StaticOrder S; S.init(gm.M, gm.N, G, bid);
;               EpiGate E{hbuf, adal + 2 * DM, gr.xr0}; pg8::gemm_phase<EpiGate>(tid, lds, gm, S, E); }
;             if (gr.samp) { const int tid = opaque_tid(wave_s); const int w = __builtin_amdgcn_readfirstlane(tid >> 6);
;               skinny_tiles(tid, lds, merged + (size_t)GPR * 2048, 2048, wt + WT_O, 2048, w * 4, 4, G, bid, SkNoPre{}, SkGateFin{hbuf, adal + 2 * DM}); }
;             PH_END
.LBB0_5340:
	v_readlane_b32 s0, v255, 45
	s_add_i32 s26, s0, 7
	v_readlane_b32 s0, v253, 6
	v_readlane_b32 s1, v253, 7
	s_cmp_ge_i32 s26, s1
	s_cbranch_scc1 .Lm7_nobar
	v_readlane_b32 s0, v255, 44
	s_cmp_lg_u32 s0, 0
	s_cbranch_scc1 .LBB0_5341
.Lm7_nobar:
	s_getpc_b64 s[98:99]
